# v25 + dilated-attention QK phase reads grouped per k-step with counted waits (K0,Q then K1) and alternate Q buffer + SwiGLU epilogue rstd reductions via v_permlane16/32_swap
# speedup vs baseline: 1.0067x; 1.0014x over previous
.LBB0_228:
	s_cmp_eq_u32 s92, s84
	s_cselect_b64 s[16:17], -1, 0
	s_cmp_lg_u32 s92, s84
	s_cselect_b64 s[18:19], -1, 0
	s_lshl_b32 s5, s92, 6
	v_or_b32_e32 v0, s5, v179
	v_sub_u32_e32 v4, v153, v0
	v_cvt_f32_i32_e32 v0, v4
	v_cndmask_b32_e64 v1, v206, 0, s[16:17]
	s_mov_b32 s20, 2.0
	s_mov_b32 s22, 0x41200000
	v_fma_f32 v10, -v144, v0, -v1
	ds_read_b128 v[0:3], v180
	ds_read_b128 v[6:9], v176
	s_mov_b32 s24, 0x41800000
	s_mov_b32 s28, 0x41900000
	s_mov_b32 s21, 0x40400000
	s_mov_b32 s23, 0x41300000
	s_mov_b32 s25, 0x41880000
	s_mov_b32 s29, 0x41980000
	v_add_f32_e32 v14, v204, v10
	v_fma_f32 v96, 0, v144, v10
	v_add_f32_e32 v97, v144, v10
	v_pk_fma_f32 v[98:99], v[144:145], s[20:21], v[10:11] op_sel_hi:[1,1,0]
	v_pk_fma_f32 v[100:101], v[144:145], s[38:39], v[10:11] op_sel_hi:[1,1,0]
	v_pk_fma_f32 v[102:103], v[144:145], s[22:23], v[10:11] op_sel_hi:[1,1,0]
	v_pk_fma_f32 v[104:105], v[144:145], s[24:25], v[10:11] op_sel_hi:[1,1,0]
	v_pk_fma_f32 v[106:107], v[144:145], s[28:29], v[10:11] op_sel_hi:[1,1,0]
	v_pk_fma_f32 v[108:109], v[144:145], s[26:27], v[10:11] op_sel_hi:[1,1,0]
	v_pk_fma_f32 v[110:111], v[144:145], s[36:37], v[10:11] op_sel_hi:[1,1,0]
	ds_read_b128 v[10:13], v180 offset:8704
	v_fma_f32 v80, 0, v144, v14
	s_waitcnt lgkmcnt(1)
	v_mfma_f32_32x32x16_bf16 v[96:111], v[0:3], v[6:9], v[96:111]
	v_add_f32_e32 v81, v144, v14
	v_fma_f32 v82, v144, s20, v14
	v_fma_f32 v83, v145, s21, v14
	v_fma_f32 v84, v144, s38, v14
	v_fma_f32 v85, v145, s39, v14
	v_pk_fma_f32 v[86:87], v[144:145], s[22:23], v[14:15] op_sel_hi:[1,1,0]
	v_pk_fma_f32 v[88:89], v[144:145], s[24:25], v[14:15] op_sel_hi:[1,1,0]
	v_pk_fma_f32 v[90:91], v[144:145], s[28:29], v[14:15] op_sel_hi:[1,1,0]
	v_pk_fma_f32 v[92:93], v[144:145], s[26:27], v[14:15] op_sel_hi:[1,1,0]
	v_pk_fma_f32 v[94:95], v[144:145], s[36:37], v[14:15] op_sel_hi:[1,1,0]
	s_or_b32 s4, s5, 63
	s_sub_i32 s20, s49, s4
	s_waitcnt lgkmcnt(0)
	v_mfma_f32_32x32x16_bf16 v[80:95], v[10:13], v[6:9], v[80:95]
	ds_read_b128 v[0:3], v180 offset:32
	ds_read_b128 v[246:249], v176 offset:32
	ds_read_b128 v[10:13], v180 offset:8736
	s_mov_b32 s4, 0
	s_cmpk_gt_i32 s20, 0x200
	s_waitcnt lgkmcnt(1)
	v_mfma_f32_32x32x16_bf16 v[96:111], v[0:3], v[246:249], v[96:111]
	s_waitcnt lgkmcnt(0)
	v_mfma_f32_32x32x16_bf16 v[80:95], v[10:13], v[246:249], v[80:95]
	ds_read_b128 v[0:3], v180 offset:64
	ds_read_b128 v[6:9], v176 offset:64
	ds_read_b128 v[10:13], v180 offset:8768
	s_waitcnt lgkmcnt(1)
	v_mfma_f32_32x32x16_bf16 v[96:111], v[0:3], v[6:9], v[96:111]
	s_waitcnt lgkmcnt(0)
	v_mfma_f32_32x32x16_bf16 v[80:95], v[10:13], v[6:9], v[80:95]
	ds_read_b128 v[0:3], v180 offset:96
	ds_read_b128 v[246:249], v176 offset:96
	ds_read_b128 v[10:13], v180 offset:8800
	s_waitcnt lgkmcnt(1)
	v_mfma_f32_32x32x16_bf16 v[96:111], v[0:3], v[246:249], v[96:111]
	s_waitcnt lgkmcnt(0)
	v_mfma_f32_32x32x16_bf16 v[80:95], v[10:13], v[246:249], v[80:95]
	ds_read_b128 v[0:3], v180 offset:128
	ds_read_b128 v[6:9], v176 offset:128
	ds_read_b128 v[10:13], v180 offset:8832
	s_waitcnt lgkmcnt(1)
	v_mfma_f32_32x32x16_bf16 v[96:111], v[0:3], v[6:9], v[96:111]
	s_waitcnt lgkmcnt(0)
	v_mfma_f32_32x32x16_bf16 v[80:95], v[10:13], v[6:9], v[80:95]
	ds_read_b128 v[0:3], v180 offset:160
	ds_read_b128 v[246:249], v176 offset:160
	ds_read_b128 v[10:13], v180 offset:8864
	s_waitcnt lgkmcnt(1)
	v_mfma_f32_32x32x16_bf16 v[96:111], v[0:3], v[246:249], v[96:111]
	s_waitcnt lgkmcnt(0)
	v_mfma_f32_32x32x16_bf16 v[80:95], v[10:13], v[246:249], v[80:95]
	ds_read_b128 v[0:3], v180 offset:192
	ds_read_b128 v[6:9], v176 offset:192
	ds_read_b128 v[10:13], v180 offset:8896
	s_waitcnt lgkmcnt(1)
	v_mfma_f32_32x32x16_bf16 v[96:111], v[0:3], v[6:9], v[96:111]
	s_waitcnt lgkmcnt(0)
	v_mfma_f32_32x32x16_bf16 v[80:95], v[10:13], v[6:9], v[80:95]
	ds_read_b128 v[0:3], v180 offset:224
	ds_read_b128 v[246:249], v176 offset:224
	ds_read_b128 v[10:13], v180 offset:8928
	s_waitcnt lgkmcnt(1)
	v_mfma_f32_32x32x16_bf16 v[96:111], v[0:3], v[246:249], v[96:111]
	s_waitcnt lgkmcnt(0)
	v_mfma_f32_32x32x16_bf16 v[80:95], v[10:13], v[246:249], v[80:95]
	s_nop 1
	s_cbranch_scc1 .LBB0_230
	s_sub_i32 s24, s46, s5
	s_cmpk_gt_i32 s20, 0x80
	s_cselect_b64 s[4:5], -1, 0
	s_cmpk_lt_i32 s24, 0x201
	s_cselect_b64 s[22:23], -1, 0
	s_and_b64 s[4:5], s[4:5], s[22:23]
	s_cmp_gt_i32 s20, -1
	s_cselect_b64 s[20:21], -1, 0
	s_cmpk_lt_i32 s24, 0x81
	s_cselect_b64 s[22:23], -1, 0
	s_and_b64 s[20:21], s[20:21], s[22:23]
	s_and_b64 s[20:21], s[20:21], exec
	s_cselect_b32 s20, 2, 3
	s_and_b64 s[4:5], s[4:5], exec
	s_cselect_b32 s4, 1, s20

.LBB0_429:
	s_cmp_eq_u32 s4, s84
	s_cselect_b64 s[16:17], -1, 0
	s_cmp_lg_u32 s4, s84
	s_cselect_b64 s[18:19], -1, 0
	s_lshl_b32 s5, s4, 6
	v_or_b32_e32 v0, s5, v179
	v_sub_u32_e32 v4, v153, v0
	v_cvt_f32_i32_e32 v0, v4
	v_cndmask_b32_e64 v1, v206, 0, s[16:17]
	s_mov_b32 s20, 2.0
	s_mov_b32 s22, 0x41200000
	v_fma_f32 v10, -v144, v0, -v1
	ds_read_b128 v[0:3], v180 offset:17408
	ds_read_b128 v[6:9], v176
	s_mov_b32 s24, 0x41800000
	s_mov_b32 s28, 0x41900000
	s_mov_b32 s21, 0x40400000
	s_mov_b32 s23, 0x41300000
	s_mov_b32 s25, 0x41880000
	s_mov_b32 s29, 0x41980000
	v_add_f32_e32 v14, v204, v10
	v_fma_f32 v96, 0, v144, v10
	v_add_f32_e32 v97, v144, v10
	v_pk_fma_f32 v[98:99], v[144:145], s[20:21], v[10:11] op_sel_hi:[1,1,0]
	v_pk_fma_f32 v[100:101], v[144:145], s[38:39], v[10:11] op_sel_hi:[1,1,0]
	v_pk_fma_f32 v[102:103], v[144:145], s[22:23], v[10:11] op_sel_hi:[1,1,0]
	v_pk_fma_f32 v[104:105], v[144:145], s[24:25], v[10:11] op_sel_hi:[1,1,0]
	v_pk_fma_f32 v[106:107], v[144:145], s[28:29], v[10:11] op_sel_hi:[1,1,0]
	v_pk_fma_f32 v[108:109], v[144:145], s[26:27], v[10:11] op_sel_hi:[1,1,0]
	v_pk_fma_f32 v[110:111], v[144:145], s[36:37], v[10:11] op_sel_hi:[1,1,0]
	ds_read_b128 v[10:13], v180 offset:26112
	v_fma_f32 v80, 0, v144, v14
	s_waitcnt lgkmcnt(1)
	v_mfma_f32_32x32x16_bf16 v[96:111], v[0:3], v[6:9], v[96:111]
	v_add_f32_e32 v81, v144, v14
	v_fma_f32 v82, v144, s20, v14
	v_fma_f32 v83, v145, s21, v14
	v_fma_f32 v84, v144, s38, v14
	v_fma_f32 v85, v145, s39, v14
	v_pk_fma_f32 v[86:87], v[144:145], s[22:23], v[14:15] op_sel_hi:[1,1,0]
	v_pk_fma_f32 v[88:89], v[144:145], s[24:25], v[14:15] op_sel_hi:[1,1,0]
	v_pk_fma_f32 v[90:91], v[144:145], s[28:29], v[14:15] op_sel_hi:[1,1,0]
	v_pk_fma_f32 v[92:93], v[144:145], s[26:27], v[14:15] op_sel_hi:[1,1,0]
	v_pk_fma_f32 v[94:95], v[144:145], s[36:37], v[14:15] op_sel_hi:[1,1,0]
	s_or_b32 s4, s5, 63
	s_sub_i32 s20, s49, s4
	s_waitcnt lgkmcnt(0)
	v_mfma_f32_32x32x16_bf16 v[80:95], v[10:13], v[6:9], v[80:95]
	ds_read_b128 v[0:3], v180 offset:17440
	ds_read_b128 v[246:249], v176 offset:32
	ds_read_b128 v[10:13], v180 offset:26144
	s_mov_b32 s4, 0
	s_cmpk_gt_i32 s20, 0x200
	s_waitcnt lgkmcnt(1)
	v_mfma_f32_32x32x16_bf16 v[96:111], v[0:3], v[246:249], v[96:111]
	s_waitcnt lgkmcnt(0)
	v_mfma_f32_32x32x16_bf16 v[80:95], v[10:13], v[246:249], v[80:95]
	ds_read_b128 v[0:3], v180 offset:17472
	ds_read_b128 v[6:9], v176 offset:64
	ds_read_b128 v[10:13], v180 offset:26176
	s_waitcnt lgkmcnt(1)
	v_mfma_f32_32x32x16_bf16 v[96:111], v[0:3], v[6:9], v[96:111]
	s_waitcnt lgkmcnt(0)
	v_mfma_f32_32x32x16_bf16 v[80:95], v[10:13], v[6:9], v[80:95]
	ds_read_b128 v[0:3], v180 offset:17504
	ds_read_b128 v[246:249], v176 offset:96
	ds_read_b128 v[10:13], v180 offset:26208
	s_waitcnt lgkmcnt(1)
	v_mfma_f32_32x32x16_bf16 v[96:111], v[0:3], v[246:249], v[96:111]
	s_waitcnt lgkmcnt(0)
	v_mfma_f32_32x32x16_bf16 v[80:95], v[10:13], v[246:249], v[80:95]
	ds_read_b128 v[0:3], v180 offset:17536
	ds_read_b128 v[6:9], v176 offset:128
	ds_read_b128 v[10:13], v180 offset:26240
	s_waitcnt lgkmcnt(1)
	v_mfma_f32_32x32x16_bf16 v[96:111], v[0:3], v[6:9], v[96:111]
	s_waitcnt lgkmcnt(0)
	v_mfma_f32_32x32x16_bf16 v[80:95], v[10:13], v[6:9], v[80:95]
	ds_read_b128 v[0:3], v180 offset:17568
	ds_read_b128 v[246:249], v176 offset:160
	ds_read_b128 v[10:13], v180 offset:26272
	s_waitcnt lgkmcnt(1)
	v_mfma_f32_32x32x16_bf16 v[96:111], v[0:3], v[246:249], v[96:111]
	s_waitcnt lgkmcnt(0)
	v_mfma_f32_32x32x16_bf16 v[80:95], v[10:13], v[246:249], v[80:95]
	ds_read_b128 v[0:3], v180 offset:17600
	ds_read_b128 v[6:9], v176 offset:192
	ds_read_b128 v[10:13], v180 offset:26304
	s_waitcnt lgkmcnt(1)
	v_mfma_f32_32x32x16_bf16 v[96:111], v[0:3], v[6:9], v[96:111]
	s_waitcnt lgkmcnt(0)
	v_mfma_f32_32x32x16_bf16 v[80:95], v[10:13], v[6:9], v[80:95]
	ds_read_b128 v[0:3], v180 offset:17632
	ds_read_b128 v[246:249], v176 offset:224
	ds_read_b128 v[10:13], v180 offset:26336
	s_waitcnt lgkmcnt(1)
	v_mfma_f32_32x32x16_bf16 v[96:111], v[0:3], v[246:249], v[96:111]
	s_waitcnt lgkmcnt(0)
	v_mfma_f32_32x32x16_bf16 v[80:95], v[10:13], v[246:249], v[80:95]
	s_nop 1
	s_cbranch_scc1 .LBB0_431
	s_sub_i32 s24, s46, s5
	s_cmpk_gt_i32 s20, 0x80
	s_cselect_b64 s[4:5], -1, 0
	s_cmpk_lt_i32 s24, 0x201
	s_cselect_b64 s[22:23], -1, 0
	s_and_b64 s[4:5], s[4:5], s[22:23]
	s_cmp_gt_i32 s20, -1
	s_cselect_b64 s[20:21], -1, 0
	s_cmpk_lt_i32 s24, 0x81
	s_cselect_b64 s[22:23], -1, 0
	s_and_b64 s[20:21], s[20:21], s[22:23]
	s_and_b64 s[20:21], s[20:21], exec
	s_cselect_b32 s20, 2, 3
	s_and_b64 s[4:5], s[4:5], exec
	s_cselect_b32 s4, 1, s20

.LBB0_771:
	s_cmp_eq_u32 s92, s84
	s_cselect_b64 s[16:17], -1, 0
	s_cmp_lg_u32 s92, s84
	s_cselect_b64 s[18:19], -1, 0
	s_lshl_b32 s5, s92, 6
	v_or_b32_e32 v0, s5, v179
	v_sub_u32_e32 v4, v153, v0
	v_cvt_f32_i32_e32 v0, v4
	v_cndmask_b32_e64 v1, v206, 0, s[16:17]
	v_add_u32_e32 v15, s46, v180
	s_mov_b32 s20, 2.0
	v_fma_f32 v10, -v144, v0, -v1
	ds_read_b128 v[0:3], v15
	s_mov_b32 s22, 0x41200000
	s_mov_b32 s24, 0x41800000
	s_mov_b32 s28, 0x41900000
	s_mov_b32 s21, 0x40400000
	s_mov_b32 s23, 0x41300000
	s_mov_b32 s25, 0x41880000
	s_mov_b32 s29, 0x41980000
	v_add_f32_e32 v14, v204, v10
	v_fma_f32 v96, 0, v144, v10
	v_add_f32_e32 v97, v144, v10
	v_pk_fma_f32 v[98:99], v[144:145], s[20:21], v[10:11] op_sel_hi:[1,1,0]
	v_pk_fma_f32 v[100:101], v[144:145], s[38:39], v[10:11] op_sel_hi:[1,1,0]
	v_pk_fma_f32 v[102:103], v[144:145], s[22:23], v[10:11] op_sel_hi:[1,1,0]
	v_pk_fma_f32 v[104:105], v[144:145], s[24:25], v[10:11] op_sel_hi:[1,1,0]
	v_pk_fma_f32 v[106:107], v[144:145], s[28:29], v[10:11] op_sel_hi:[1,1,0]
	v_pk_fma_f32 v[108:109], v[144:145], s[26:27], v[10:11] op_sel_hi:[1,1,0]
	v_pk_fma_f32 v[110:111], v[144:145], s[36:37], v[10:11] op_sel_hi:[1,1,0]
	ds_read_b128 v[10:13], v15 offset:8704
	ds_read_b128 v[6:9], v176
	s_waitcnt lgkmcnt(0)
	v_mfma_f32_32x32x16_bf16 v[96:111], v[0:3], v[6:9], v[96:111]
	v_fma_f32 v80, 0, v144, v14
	v_add_f32_e32 v81, v144, v14
	v_fma_f32 v82, v144, s20, v14
	v_fma_f32 v83, v145, s21, v14
	v_fma_f32 v84, v144, s38, v14
	v_fma_f32 v85, v145, s39, v14
	v_pk_fma_f32 v[86:87], v[144:145], s[22:23], v[14:15] op_sel_hi:[1,1,0]
	v_pk_fma_f32 v[88:89], v[144:145], s[24:25], v[14:15] op_sel_hi:[1,1,0]
	v_pk_fma_f32 v[90:91], v[144:145], s[28:29], v[14:15] op_sel_hi:[1,1,0]
	v_pk_fma_f32 v[92:93], v[144:145], s[26:27], v[14:15] op_sel_hi:[1,1,0]
	v_pk_fma_f32 v[94:95], v[144:145], s[36:37], v[14:15] op_sel_hi:[1,1,0]
	s_or_b32 s4, s5, 63
	s_sub_i32 s20, s49, s4
	v_mfma_f32_32x32x16_bf16 v[80:95], v[10:13], v[6:9], v[80:95]
	ds_read_b128 v[0:3], v15 offset:32
	ds_read_b128 v[246:249], v176 offset:32
	ds_read_b128 v[10:13], v15 offset:8736
	s_mov_b32 s4, 0
	s_cmpk_gt_i32 s20, 0x200
	s_waitcnt lgkmcnt(1)
	v_mfma_f32_32x32x16_bf16 v[96:111], v[0:3], v[246:249], v[96:111]
	s_waitcnt lgkmcnt(0)
	v_mfma_f32_32x32x16_bf16 v[80:95], v[10:13], v[246:249], v[80:95]
	ds_read_b128 v[0:3], v15 offset:64
	ds_read_b128 v[6:9], v176 offset:64
	ds_read_b128 v[10:13], v15 offset:8768
	s_waitcnt lgkmcnt(1)
	v_mfma_f32_32x32x16_bf16 v[96:111], v[0:3], v[6:9], v[96:111]
	s_waitcnt lgkmcnt(0)
	v_mfma_f32_32x32x16_bf16 v[80:95], v[10:13], v[6:9], v[80:95]
	ds_read_b128 v[0:3], v15 offset:96
	ds_read_b128 v[246:249], v176 offset:96
	ds_read_b128 v[10:13], v15 offset:8800
	s_waitcnt lgkmcnt(1)
	v_mfma_f32_32x32x16_bf16 v[96:111], v[0:3], v[246:249], v[96:111]
	s_waitcnt lgkmcnt(0)
	v_mfma_f32_32x32x16_bf16 v[80:95], v[10:13], v[246:249], v[80:95]
	ds_read_b128 v[0:3], v15 offset:128
	ds_read_b128 v[6:9], v176 offset:128
	ds_read_b128 v[10:13], v15 offset:8832
	s_waitcnt lgkmcnt(1)
	v_mfma_f32_32x32x16_bf16 v[96:111], v[0:3], v[6:9], v[96:111]
	s_waitcnt lgkmcnt(0)
	v_mfma_f32_32x32x16_bf16 v[80:95], v[10:13], v[6:9], v[80:95]
	ds_read_b128 v[0:3], v15 offset:160
	ds_read_b128 v[246:249], v176 offset:160
	ds_read_b128 v[10:13], v15 offset:8864
	s_waitcnt lgkmcnt(1)
	v_mfma_f32_32x32x16_bf16 v[96:111], v[0:3], v[246:249], v[96:111]
	s_waitcnt lgkmcnt(0)
	v_mfma_f32_32x32x16_bf16 v[80:95], v[10:13], v[246:249], v[80:95]
	ds_read_b128 v[0:3], v15 offset:192
	ds_read_b128 v[6:9], v176 offset:192
	ds_read_b128 v[10:13], v15 offset:8896
	s_waitcnt lgkmcnt(1)
	v_mfma_f32_32x32x16_bf16 v[96:111], v[0:3], v[6:9], v[96:111]
	s_waitcnt lgkmcnt(0)
	v_mfma_f32_32x32x16_bf16 v[80:95], v[10:13], v[6:9], v[80:95]
	ds_read_b128 v[0:3], v15 offset:224
	ds_read_b128 v[246:249], v176 offset:224
	ds_read_b128 v[10:13], v15 offset:8928
	s_waitcnt lgkmcnt(1)
	v_mfma_f32_32x32x16_bf16 v[96:111], v[0:3], v[246:249], v[96:111]
	s_waitcnt lgkmcnt(0)
	v_mfma_f32_32x32x16_bf16 v[80:95], v[10:13], v[246:249], v[80:95]
	s_nop 1
	s_cbranch_scc1 .LBB0_773
	s_sub_i32 s24, s93, s5
	s_cmpk_gt_i32 s20, 0x80
	s_cselect_b64 s[4:5], -1, 0
	s_cmpk_lt_i32 s24, 0x201
	s_cselect_b64 s[22:23], -1, 0
	s_and_b64 s[4:5], s[4:5], s[22:23]
	s_cmp_gt_i32 s20, -1
	s_cselect_b64 s[20:21], -1, 0
	s_cmpk_lt_i32 s24, 0x81
	s_cselect_b64 s[22:23], -1, 0
	s_and_b64 s[20:21], s[20:21], s[22:23]
	s_and_b64 s[20:21], s[20:21], exec
	s_cselect_b32 s20, 2, 3
	s_and_b64 s[4:5], s[4:5], exec
	s_cselect_b32 s4, 1, s20

.LBB0_972:
	s_cmp_eq_u32 s4, s84
	s_cselect_b64 s[16:17], -1, 0
	s_cmp_lg_u32 s4, s84
	s_cselect_b64 s[18:19], -1, 0
	s_lshl_b32 s5, s4, 6
	v_or_b32_e32 v0, s5, v179
	v_sub_u32_e32 v4, v153, v0
	v_cvt_f32_i32_e32 v0, v4
	v_cndmask_b32_e64 v1, v206, 0, s[16:17]
	v_add_u32_e32 v15, s44, v180
	s_mov_b32 s20, 2.0
	v_fma_f32 v10, -v144, v0, -v1
	ds_read_b128 v[0:3], v15
	s_mov_b32 s22, 0x41200000
	s_mov_b32 s24, 0x41800000
	s_mov_b32 s28, 0x41900000
	s_mov_b32 s21, 0x40400000
	s_mov_b32 s23, 0x41300000
	s_mov_b32 s25, 0x41880000
	s_mov_b32 s29, 0x41980000
	v_add_f32_e32 v14, v204, v10
	v_fma_f32 v96, 0, v144, v10
	v_add_f32_e32 v97, v144, v10
	v_pk_fma_f32 v[98:99], v[144:145], s[20:21], v[10:11] op_sel_hi:[1,1,0]
	v_pk_fma_f32 v[100:101], v[144:145], s[38:39], v[10:11] op_sel_hi:[1,1,0]
	v_pk_fma_f32 v[102:103], v[144:145], s[22:23], v[10:11] op_sel_hi:[1,1,0]
	v_pk_fma_f32 v[104:105], v[144:145], s[24:25], v[10:11] op_sel_hi:[1,1,0]
	v_pk_fma_f32 v[106:107], v[144:145], s[28:29], v[10:11] op_sel_hi:[1,1,0]
	v_pk_fma_f32 v[108:109], v[144:145], s[26:27], v[10:11] op_sel_hi:[1,1,0]
	v_pk_fma_f32 v[110:111], v[144:145], s[36:37], v[10:11] op_sel_hi:[1,1,0]
	ds_read_b128 v[10:13], v15 offset:8704
	ds_read_b128 v[6:9], v176
	s_waitcnt lgkmcnt(0)
	v_mfma_f32_32x32x16_bf16 v[96:111], v[0:3], v[6:9], v[96:111]
	v_fma_f32 v80, 0, v144, v14
	v_add_f32_e32 v81, v144, v14
	v_fma_f32 v82, v144, s20, v14
	v_fma_f32 v83, v145, s21, v14
	v_fma_f32 v84, v144, s38, v14
	v_fma_f32 v85, v145, s39, v14
	v_pk_fma_f32 v[86:87], v[144:145], s[22:23], v[14:15] op_sel_hi:[1,1,0]
	v_pk_fma_f32 v[88:89], v[144:145], s[24:25], v[14:15] op_sel_hi:[1,1,0]
	v_pk_fma_f32 v[90:91], v[144:145], s[28:29], v[14:15] op_sel_hi:[1,1,0]
	v_pk_fma_f32 v[92:93], v[144:145], s[26:27], v[14:15] op_sel_hi:[1,1,0]
	v_pk_fma_f32 v[94:95], v[144:145], s[36:37], v[14:15] op_sel_hi:[1,1,0]
	s_or_b32 s4, s5, 63
	s_sub_i32 s20, s49, s4
	v_mfma_f32_32x32x16_bf16 v[80:95], v[10:13], v[6:9], v[80:95]
	ds_read_b128 v[0:3], v15 offset:32
	ds_read_b128 v[246:249], v176 offset:32
	ds_read_b128 v[10:13], v15 offset:8736
	s_mov_b32 s4, 0
	s_cmpk_gt_i32 s20, 0x200
	s_waitcnt lgkmcnt(1)
	v_mfma_f32_32x32x16_bf16 v[96:111], v[0:3], v[246:249], v[96:111]
	s_waitcnt lgkmcnt(0)
	v_mfma_f32_32x32x16_bf16 v[80:95], v[10:13], v[246:249], v[80:95]
	ds_read_b128 v[0:3], v15 offset:64
	ds_read_b128 v[6:9], v176 offset:64
	ds_read_b128 v[10:13], v15 offset:8768
	s_waitcnt lgkmcnt(1)
	v_mfma_f32_32x32x16_bf16 v[96:111], v[0:3], v[6:9], v[96:111]
	s_waitcnt lgkmcnt(0)
	v_mfma_f32_32x32x16_bf16 v[80:95], v[10:13], v[6:9], v[80:95]
	ds_read_b128 v[0:3], v15 offset:96
	ds_read_b128 v[246:249], v176 offset:96
	ds_read_b128 v[10:13], v15 offset:8800
	s_waitcnt lgkmcnt(1)
	v_mfma_f32_32x32x16_bf16 v[96:111], v[0:3], v[246:249], v[96:111]
	s_waitcnt lgkmcnt(0)
	v_mfma_f32_32x32x16_bf16 v[80:95], v[10:13], v[246:249], v[80:95]
	ds_read_b128 v[0:3], v15 offset:128
	ds_read_b128 v[6:9], v176 offset:128
	ds_read_b128 v[10:13], v15 offset:8832
	s_waitcnt lgkmcnt(1)
	v_mfma_f32_32x32x16_bf16 v[96:111], v[0:3], v[6:9], v[96:111]
	s_waitcnt lgkmcnt(0)
	v_mfma_f32_32x32x16_bf16 v[80:95], v[10:13], v[6:9], v[80:95]
	ds_read_b128 v[0:3], v15 offset:160
	ds_read_b128 v[246:249], v176 offset:160
	ds_read_b128 v[10:13], v15 offset:8864
	s_waitcnt lgkmcnt(1)
	v_mfma_f32_32x32x16_bf16 v[96:111], v[0:3], v[246:249], v[96:111]
	s_waitcnt lgkmcnt(0)
	v_mfma_f32_32x32x16_bf16 v[80:95], v[10:13], v[246:249], v[80:95]
	ds_read_b128 v[0:3], v15 offset:192
	ds_read_b128 v[6:9], v176 offset:192
	ds_read_b128 v[10:13], v15 offset:8896
	s_waitcnt lgkmcnt(1)
	v_mfma_f32_32x32x16_bf16 v[96:111], v[0:3], v[6:9], v[96:111]
	s_waitcnt lgkmcnt(0)
	v_mfma_f32_32x32x16_bf16 v[80:95], v[10:13], v[6:9], v[80:95]
	ds_read_b128 v[0:3], v15 offset:224
	ds_read_b128 v[246:249], v176 offset:224
	ds_read_b128 v[10:13], v15 offset:8928
	s_waitcnt lgkmcnt(1)
	v_mfma_f32_32x32x16_bf16 v[96:111], v[0:3], v[246:249], v[96:111]
	s_waitcnt lgkmcnt(0)
	v_mfma_f32_32x32x16_bf16 v[80:95], v[10:13], v[246:249], v[80:95]
	s_nop 1
	s_cbranch_scc1 .LBB0_974
	s_sub_i32 s24, s93, s5
	s_cmpk_gt_i32 s20, 0x80
	s_cselect_b64 s[4:5], -1, 0
	s_cmpk_lt_i32 s24, 0x201
	s_cselect_b64 s[22:23], -1, 0
	s_and_b64 s[4:5], s[4:5], s[22:23]
	s_cmp_gt_i32 s20, -1
	s_cselect_b64 s[20:21], -1, 0
	s_cmpk_lt_i32 s24, 0x81
	s_cselect_b64 s[22:23], -1, 0
	s_and_b64 s[20:21], s[20:21], s[22:23]
	s_and_b64 s[20:21], s[20:21], exec
	s_cselect_b32 s20, 2, 3
	s_and_b64 s[4:5], s[4:5], exec
	s_cselect_b32 s4, 1, s20
